# RWKV operands stage: the five operand ds_read_b128 issued before the first lgkmcnt wait (one exposed LDS round trip per chunk removed), on top of v36
# speedup vs baseline: 1.0042x; 1.0042x over previous
; __device__ __forceinline__ void rwkv_chain(LAS unsigned char* lds, int cid, const bf16_t* P0, const float* mu, const float* w0, const float* w2, const float* a0, const float* a2, ...
;     ...
;         { RW_IDS const int s = tid >> 4, c0 = (tid & 15) * 4; const int tok = dir ? 31 - s : s, tokp = dir ? tok + 1 : tok - 1;
;           const f32x4 cum = *(const LAS f32x4*)(wS + tok * 64 + c0); f32x4 cump = (f32x4){0.f, 0.f, 0.f, 0.f}; if (s > 0) cump = *(const LAS f32x4*)(wS + tokp * 64 + c0);
;           const f32x4 nk4 = *(const LAS f32x4*)(nkS + tok * 64 + c0), b4 = *(const LAS f32x4*)(bS + tok * 64 + c0), k4 = *(const LAS f32x4*)(kS + tok * 64 + c0), r4 = *(const LAS f32x4*)(rS + tok * 64 + c0), v4 = *(const LAS f32x4*)(vS + tok * 64 + c0);
;           float ta[4], tb[4], tk[4], tr[4];
; #pragma unroll
;           for (int i = 0; i < 4; ++i) { const float g = __expf(cum[i]), gp = __expf(cump[i]), ig = __expf(-cum[i]);
;               ta[i] = nk4[i] * gp; tb[i] = b4[i] * ig; tk[i] = k4[i] * ig; tr[i] = r4[i] * g;
;               BtT[(c0 + i) * 40 + s] = (bf16_t)f2bf(tb[i]); KtT[(c0 + i) * 40 + s] = (bf16_t)f2bf(tk[i]); VT[(c0 + i) * 40 + s] = (bf16_t)f2bf(v4[i]);
;               if (s == 31) gL[c0 + i] = g; }
;           u32x2 w; w.x = pk2(ta[0], ta[1]); w.y = pk2(ta[2], ta[3]); *(LAS u32x2*)(At + s * 72 + c0) = w;
;           w.x = pk2(tb[0], tb[1]); w.y = pk2(tb[2], tb[3]); *(LAS u32x2*)(Bt + s * 72 + c0) = w;
;           w.x = pk2(tk[0], tk[1]); w.y = pk2(tk[2], tk[3]); *(LAS u32x2*)(Kt + s * 72 + c0) = w;
;           w.x = pk2(tr[0], tr[1]); w.y = pk2(tr[2], tr[3]); *(LAS u32x2*)(Rt + s * 72 + c0) = w; }
;         __syncthreads();
;         { RW_IDS const int mat = wid >> 1, mt = wid & 1; const LAS bf16_t* Aop = (mat < 2) ? At : Rt; const LAS bf16_t* Bop = (mat & 1) ? Kt : Bt;
; #pragma unroll
;           for (int nt = 0; nt < 2; ++nt) { f32x4 acc = (f32x4){0.f, 0.f, 0.f, 0.f};
; #pragma unroll
;               for (int ks = 0; ks < 2; ++ks) acc = mfma16(ldsfrag(Bop, 72, nt * 16, ks * 32, fr, fq), ldsfrag(Aop, 72, mt * 16, ks * 32, fr, fq), acc);
;               const int srow = mt * 16 + fr;
; #pragma unroll
;               for (int e = 0; e < 4; ++e) { const int i = nt * 16 + fq * 4 + e; const bool keep = (mat < 2) ? (i < srow) : (i <= srow); if (!keep) acc[e] = 0.f; }
;               if (mat == 0) {
; #pragma unroll
.Lrw_pf2_done:
	v_mov_b32_e32 v8, v200
	s_waitcnt lgkmcnt(0)
	s_barrier
	v_mov_b32_e32 v9, 0
	v_ashrrev_i32_e32 v39, 4, v8
	v_lshlrev_b32_e32 v8, 2, v8
	v_and_b32_e32 v114, 60, v8
	v_sub_u32_e32 v8, 31, v39
	v_cndmask_b32_e64 v12, v39, v8, s[10:11]
	v_lshlrev_b32_e32 v8, 8, v12
	v_lshlrev_b32_e32 v13, 2, v114
	v_add3_u32 v24, 0, v8, v13
	ds_read_b128 v[20:23], v24 offset:24576
	v_cmp_lt_i32_e32 vcc, 0, v39
	v_mov_b32_e32 v8, 0
	v_mov_b32_e32 v10, 0
	v_mov_b32_e32 v11, 0
	s_and_saveexec_b64 s[12:13], vcc
	v_add_lshl_u32 v8, v12, s90, 8
	v_add3_u32 v8, 0, v8, v13
	ds_read_b128 v[8:11], v8 offset:24576
	s_or_b64 exec, exec, s[12:13]
	ds_read_b128 v[12:15], v24 offset:32768
	ds_read_b128 v[28:31], v24 offset:40960
	ds_read_b128 v[32:35], v24 offset:8192
	ds_read_b128 v[16:19], v24
	ds_read_b128 v[24:27], v24 offset:16384
	s_waitcnt lgkmcnt(5)
	v_mul_f32_e32 v115, 0xbfb8aa3b, v20
	v_exp_f32_e32 v116, v115
	v_mul_f32_e32 v20, 0x3fb8aa3b, v20
	v_exp_f32_e32 v115, v20
	s_waitcnt lgkmcnt(3)
	v_mul_f32_e32 v28, v116, v28
	s_waitcnt lgkmcnt(2)
	v_mul_f32_e32 v20, v116, v32
	v_mad_u32_u24 v116, v114, 40, v39
	v_lshl_add_u32 v116, v116, 1, 0
	v_cvt_pk_bf16_f32 v32, v28, s0
	v_add_u32_e32 v117, 0x1c400, v116
	v_cmp_eq_u32_e32 vcc, 31, v39
	ds_write_b16 v117, v32
	v_cvt_pk_bf16_f32 v32, v20, s0
	v_add_u32_e32 v118, 0x1d800, v116
	s_waitcnt lgkmcnt(1)
	v_cvt_pk_bf16_f32 v24, v24, s0
	v_add_u32_e32 v119, 0x1ec00, v116
	v_lshl_add_u32 v116, v114, 2, 0
	ds_write_b16 v118, v32
	ds_write_b16 v119, v24
	s_and_saveexec_b64 s[12:13], vcc
	v_add_u32_e32 v24, 0x25a00, v116
	ds_write_b32 v24, v115
	s_or_b64 exec, exec, s[12:13]
	v_mul_f32_e32 v24, 0xbfb8aa3b, v21
	v_exp_f32_e32 v120, v24
	v_mul_f32_e32 v21, 0x3fb8aa3b, v21
	v_exp_f32_e32 v32, v21
	v_cvt_pk_bf16_f32 v25, v25, s0
	v_mul_f32_e32 v24, v120, v29
	v_mul_f32_e32 v21, v120, v33
	v_cvt_pk_bf16_f32 v29, v24, s0
	ds_write_b16 v117, v29 offset:80
	v_cvt_pk_bf16_f32 v29, v21, s0
	ds_write_b16 v118, v29 offset:80
	ds_write_b16 v119, v25 offset:80
	s_and_saveexec_b64 s[12:13], vcc
	v_add_u32_e32 v25, 0x25a04, v116
	ds_write_b32 v25, v32
	s_or_b64 exec, exec, s[12:13]
	v_mul_f32_e32 v25, 0xbfb8aa3b, v22
	v_exp_f32_e32 v33, v25
	v_mul_f32_e32 v22, 0x3fb8aa3b, v22
	v_exp_f32_e32 v29, v22
	v_cvt_pk_bf16_f32 v26, v26, s0
	v_mul_f32_e32 v25, v33, v30
	v_mul_f32_e32 v22, v33, v34
	v_cvt_pk_bf16_f32 v30, v25, s0
	ds_write_b16 v117, v30 offset:160
	v_cvt_pk_bf16_f32 v30, v22, s0
	ds_write_b16 v118, v30 offset:160
	ds_write_b16 v119, v26 offset:160
	s_and_saveexec_b64 s[12:13], vcc
	v_add_u32_e32 v26, 0x25a08, v116
	ds_write_b32 v26, v29
	s_or_b64 exec, exec, s[12:13]
	v_mul_f32_e32 v26, 0xbfb8aa3b, v23
	v_exp_f32_e32 v33, v26
	v_mul_f32_e32 v23, 0x3fb8aa3b, v23
	v_exp_f32_e32 v30, v23
	v_cvt_pk_bf16_f32 v27, v27, s0
	v_mul_f32_e32 v26, v33, v31
	v_mul_f32_e32 v23, v33, v35
	v_cvt_pk_bf16_f32 v31, v26, s0
	ds_write_b16 v117, v31 offset:240
	v_cvt_pk_bf16_f32 v31, v23, s0
	ds_write_b16 v118, v31 offset:240
	ds_write_b16 v119, v27 offset:240
	s_and_saveexec_b64 s[12:13], vcc
	v_add_u32_e32 v27, 0x25a0c, v116
	ds_write_b32 v27, v30
	s_or_b64 exec, exec, s[12:13]
	v_mul_f32_e32 v11, 0x3fb8aa3b, v11
	v_mul_f32_e32 v10, 0x3fb8aa3b, v10
	v_mul_f32_e32 v9, 0x3fb8aa3b, v9
	v_mul_f32_e32 v8, 0x3fb8aa3b, v8
	v_exp_f32_e32 v11, v11
	v_exp_f32_e32 v10, v10
	v_exp_f32_e32 v9, v9
	v_exp_f32_e32 v8, v8
	v_mul_f32_e32 v11, v15, v11
	v_mul_f32_e32 v10, v14, v10
	v_mul_f32_e32 v9, v13, v9
	v_mul_f32_e32 v8, v12, v8
	v_cvt_pk_bf16_f32 v8, v8, v9
	v_cvt_pk_bf16_f32 v9, v10, v11
	v_mul_lo_u32 v10, v39, s76
	v_lshlrev_b32_e32 v11, 1, v114
	v_mul_f32_e32 v12, v115, v16
	v_add3_u32 v16, s79, v10, v11
	ds_write_b64 v16, v[8:9]
	v_cvt_pk_bf16_f32 v8, v28, v24
	v_cvt_pk_bf16_f32 v9, v25, v26
	v_add3_u32 v16, s80, v10, v11
	v_mul_f32_e32 v15, v30, v19
	v_mul_f32_e32 v14, v29, v18
	v_mul_f32_e32 v13, v32, v17
	ds_write_b64 v16, v[8:9]
	v_cvt_pk_bf16_f32 v8, v20, v21
	v_cvt_pk_bf16_f32 v9, v22, v23
	v_add3_u32 v16, s81, v10, v11
	ds_write_b64 v16, v[8:9]
	v_cvt_pk_bf16_f32 v8, v12, v13
	v_cvt_pk_bf16_f32 v9, v14, v15
	v_add3_u32 v10, s82, v10, v11
	ds_write_b64 v10, v[8:9]
	v_mov_b32_e32 v8, v200
	s_waitcnt lgkmcnt(0)
	s_barrier
	s_nop 0
	v_readfirstlane_b32 s7, v8
	s_ashr_i32 s48, s7, 7
	s_cmp_lt_i32 s48, 2
	s_cselect_b64 s[12:13], -1, 0
	s_and_b64 s[14:15], s[12:13], exec
	v_bfe_u32 v13, v8, 4, 2
	s_cselect_b32 s14, s79, s82
	s_bitcmp0_b32 s7, 7
	s_cselect_b32 s15, s80, s81
	v_lshlrev_b32_e32 v9, 4, v13
	v_add_u32_e32 v11, s15, v9
	s_lshr_b32 s15, s7, 2
	s_cmpk_gt_u32 s7, 0x7f
	s_cselect_b64 s[16:17], -1, 0
	s_cmp_eq_u32 s48, 2
	s_mov_b32 s7, 0x24600
	s_cselect_b32 s7, s7, 0x25000
	s_cmp_lg_u32 s48, 1
	v_and_b32_e32 v10, 15, v8
	s_cselect_b32 s7, s7, 0x23c00
	v_and_or_b32 v8, s15, 16, v10
	v_mov_b32_e32 v12, s14
	s_add_i32 s7, s7, 0
	v_mad_u32_u24 v12, v8, s76, v12
	v_mov_b32_e32 v14, s7
	v_mad_u32_u24 v22, v10, s76, v11
	v_add_u32_e32 v12, v12, v9
	v_mad_u32_u24 v26, v8, s83, v14
	ds_read_b128 v[114:117], v22
	ds_read_b128 v[118:121], v12
	ds_read_b128 v[122:125], v22 offset:64
	ds_read_b128 v[126:129], v12 offset:64
	ds_read_b128 v[130:133], v22 offset:2304
	ds_read_b128 v[134:137], v22 offset:2368
	v_lshlrev_b32_e32 v9, 2, v13
	s_cmp_gt_i32 s48, 1
	s_cselect_b32 s14, 1, 0
	v_lshlrev_b32_e32 v13, 3, v13
	v_sub_u32_e32 v27, v8, v9
	v_add_u32_e32 v13, v26, v13
	v_lshlrev_b32_e32 v28, 5, v8
	v_add_u32_e32 v27, s14, v27
	v_add3_u32 v28, s84, v28, v9
	s_waitcnt lgkmcnt(4)
	v_mfma_f32_16x16x32_bf16 v[14:17], v[114:117], v[118:121], 0
	s_waitcnt lgkmcnt(2)
	v_mfma_f32_16x16x32_bf16 v[14:17], v[122:125], v[126:129], v[14:17]
	s_waitcnt lgkmcnt(1)
	v_mfma_f32_16x16x32_bf16 v[18:21], v[130:133], v[118:121], 0
	s_waitcnt lgkmcnt(0)
	v_mfma_f32_16x16x32_bf16 v[18:21], v[134:137], v[126:129], v[18:21]
	v_cmp_lt_i32_e32 vcc, 0, v27
	v_cmp_lt_i32_e64 s[12:13], 1, v27
	v_cmp_lt_i32_e64 s[14:15], 2, v27
	v_cmp_lt_i32_e64 s[16:17], 3, v27
	v_cndmask_b32_e32 v14, 0, v14, vcc
	v_cndmask_b32_e64 v15, 0, v15, s[12:13]
	v_cndmask_b32_e64 v16, 0, v16, s[14:15]
	v_cndmask_b32_e64 v17, 0, v17, s[16:17]
	v_cmp_lt_i32_e32 vcc, 16, v27
	v_cmp_lt_i32_e64 s[12:13], 17, v27
	v_cmp_lt_i32_e64 s[14:15], 18, v27
	v_cmp_lt_i32_e64 s[16:17], 19, v27
	v_cndmask_b32_e32 v18, 0, v18, vcc
	v_cndmask_b32_e64 v19, 0, v19, s[12:13]
	v_cndmask_b32_e64 v20, 0, v20, s[14:15]
	v_cndmask_b32_e64 v21, 0, v21, s[16:17]
	s_cmp_lg_u32 s48, 0
	s_cbranch_scc0 .Lrw_s1_f32
	v_cvt_pk_bf16_f32 v22, v14, v15
	v_cvt_pk_bf16_f32 v23, v16, v17
	v_cvt_pk_bf16_f32 v24, v18, v19
	v_cvt_pk_bf16_f32 v25, v20, v21
	ds_write_b64 v13, v[22:23]
	ds_write_b64 v13, v[24:25] offset:32
	s_branch .LBB0_534
